# k17 + grid barrier: non-leader workgroups spin on the global release word (TOPGEN) instead of the per-XCD word, removing one release hop
# baseline (speedup 1.0000x reference)
; __device__ __forceinline__ unsigned xb_ld(unsigned* p)              { return __hip_atomic_load(p, __ATOMIC_RELAXED, __HIP_MEMORY_SCOPE_AGENT); }
; __device__ __forceinline__ unsigned xb_add(unsigned* p, unsigned v) { return __hip_atomic_fetch_add(p, v, __ATOMIC_RELAXED, __HIP_MEMORY_SCOPE_AGENT); }
; #define XB_SPIN(cond, bar) do { unsigned _sp = 0; while (cond) { __builtin_amdgcn_s_sleep(1); \
;     if ((++_sp & 255u) == 0u) { if (xb_ld(&(bar)[XB_TMO])) break; if (_sp > XB_SPIN_CAP) { atomicAdd(&(bar)[XB_TMO], 1u); break; } } } } while (0)
; __device__ __forceinline__ void xcd_barrier(const XcdBarrier& b) {
;     ...
;         const unsigned old = xb_add(&bar[XB_XSUB(b.x)], 1u);
;         const unsigned gen = old / nloc;
;         if (old + 1u == (gen + 1u) * nloc) {
;             __builtin_amdgcn_fence(__ATOMIC_RELEASE, "agent");
;             asm volatile("s_waitcnt vmcnt(0)" ::: "memory");
;             const unsigned og = xb_add(&bar[XB_TOP], 1u);
;             const unsigned tg = og / nx;
;             if (og + 1u == (tg + 1u) * nx) xb_add(&bar[XB_TOPGEN], 1u);
;             else XB_SPIN(xb_ld(&bar[XB_TOPGEN]) == tg, bar);
;             __builtin_amdgcn_fence(__ATOMIC_ACQUIRE, "agent");
;             xb_add(&bar[XB_XGEN(b.x)], 1u);
;             asm volatile("s_waitcnt vmcnt(0)" ::: "memory");
;         } else {
;             XB_SPIN(xb_ld(&bar[XB_XGEN(b.x)]) == gen, bar);
;             __builtin_amdgcn_fence(__ATOMIC_ACQUIRE, "agent");
;             asm volatile("s_waitcnt vmcnt(0)" ::: "memory");
;         }
.LBB0_1672:
	s_or_b64 exec, exec, s[4:5]
	v_cvt_f32_u32_e32 v4, v2
	s_waitcnt vmcnt(0)
	v_readfirstlane_b32 s4, v3
	v_sub_u32_e32 v3, 0, v2
	v_rcp_iflag_f32_e32 v4, v4
	v_add_u32_e32 v5, s4, v1
	v_mul_f32_e32 v4, 0x4f7ffffe, v4
	v_cvt_u32_f32_e32 v4, v4
	v_mul_lo_u32 v1, v3, v4
	v_mul_hi_u32 v1, v4, v1
	v_add_u32_e32 v1, v4, v1
	v_mul_hi_u32 v1, v5, v1
	v_mul_lo_u32 v3, v1, v2
	v_sub_u32_e32 v3, v5, v3
	v_add_u32_e32 v4, 1, v1
	v_cmp_ge_u32_e32 vcc, v3, v2
	s_nop 1
	v_cndmask_b32_e32 v1, v1, v4, vcc
	v_sub_u32_e32 v4, v3, v2
	v_cndmask_b32_e32 v3, v3, v4, vcc
	v_add_u32_e32 v4, 1, v1
	v_cmp_ge_u32_e32 vcc, v3, v2
	v_add_u32_e32 v3, 1, v5
	s_nop 0
	v_cndmask_b32_e32 v1, v1, v4, vcc
	v_mul_lo_u32 v4, v2, v1
	v_add_u32_e32 v2, v4, v2
	v_cmp_ne_u32_e32 vcc, v3, v2
	s_and_saveexec_b64 s[4:5], vcc
	s_xor_b64 s[4:5], exec, s[4:5]
	s_cbranch_execz .LBB0_1686
	v_readlane_b32 s6, v254, 14
	v_readlane_b32 s7, v254, 15
	s_waitcnt lgkmcnt(0)
	s_nop 3
	global_load_dword v0, v181, s[6:7] sc1
	s_waitcnt vmcnt(0)
	v_cmp_eq_u32_e32 vcc, v0, v1
	s_and_saveexec_b64 s[6:7], vcc
	s_cbranch_execz .LBB0_1685
	s_mov_b32 s18, 1
	s_mov_b64 s[8:9], 0
	s_branch .LBB0_1676

; __device__ __forceinline__ unsigned xb_ld(unsigned* p)              { return __hip_atomic_load(p, __ATOMIC_RELAXED, __HIP_MEMORY_SCOPE_AGENT); }
; #define XB_SPIN(cond, bar) do { unsigned _sp = 0; while (cond) { __builtin_amdgcn_s_sleep(1); \
;     if ((++_sp & 255u) == 0u) { if (xb_ld(&(bar)[XB_TMO])) break; if (_sp > XB_SPIN_CAP) { atomicAdd(&(bar)[XB_TMO], 1u); break; } } } } while (0)
; __device__ __forceinline__ void xcd_barrier(const XcdBarrier& b) {
;     ...
;             XB_SPIN(xb_ld(&bar[XB_XGEN(b.x)]) == gen, bar);
;             __builtin_amdgcn_fence(__ATOMIC_ACQUIRE, "agent");
;             asm volatile("s_waitcnt vmcnt(0)" ::: "memory");
.LBB0_1680:
	v_readlane_b32 s12, v254, 14
	v_readlane_b32 s13, v254, 15
	s_add_i32 s18, s18, 1
	s_mov_b64 s[14:15], -1
	s_nop 2
	global_load_dword v0, v181, s[12:13] sc1
	s_waitcnt vmcnt(0)
	v_cmp_ne_u32_e32 vcc, v0, v1
	s_orn2_b64 s[12:13], vcc, exec
	s_branch .LBB0_1675
